# attention phase: static s_setprio 1 for waves 4-7 (younger half)
# baseline (speedup 1.0000x reference)
; __device__ __forceinline__ int launder_i(int v) { v = __builtin_amdgcn_readfirstlane(v); asm volatile("" : "+s"(v)); return v; }
; __device__ __forceinline__ void p3_phase(const Params& pin, int l, unsigned char* lds) {
;     ...
;     const int nunits = (l == DEPTH - 1) ? 1024 : 1152;
;     for (int r = launder_i(((PROBE_MASK >> 9) & 1) ? 0 : 1); r < 2; ++r)
;     for (int u = blockIdx.x; u < nunits; u += gridDim.x) {
;         if (u < 1024) { const int bh = u >> 3, qt = u & 7; attn_unit(p, bh >> 3, bh & 7, CTXL + qt * 256, TPB, lds, r); }
;         else { const int bh = u - 1024; attn_unit(p, bh >> 3, bh & 7, 0, CTXL, lds, r); }
;     }
.LBB0_570:
	s_mov_b32 s38, 1
	s_cmp_gt_i32 s38, 1
	s_cbranch_scc1 .LBB0_636
	v_readfirstlane_b32 s66, v208
	s_lshr_b32 s66, s66, 6
	s_cmp_ge_u32 s66, 4
	s_cbranch_scc0 .Lattn_noprio
	s_setprio 1
.Lattn_noprio:
	s_cmp_eq_u32 s64, 3
	s_cselect_b32 s41, s29, 0x480
	v_readlane_b32 s2, v253, 0
	s_cmp_lt_i32 s2, s41
	s_cselect_b64 s[4:5], -1, 0
	s_add_u32 s44, s21, 0x669b000
	s_addc_u32 s52, s31, 0
	s_add_u32 s6, s21, 0x1a19b000
	s_addc_u32 s7, s31, 0
	s_add_u32 s8, s21, 0x1599b000
	s_addc_u32 s9, s31, 0
	s_add_u32 s42, s21, 0x17d9b000
	s_addc_u32 s43, s31, 0
	s_add_u32 s46, s21, 0x1a19d000
	s_addc_u32 s47, s31, 0
	s_add_u32 s48, s21, 0x17d9b100
	s_addc_u32 s49, s31, 0
	s_add_u32 s50, s21, 0x159bb000
	s_addc_u32 s51, s31, 0
	s_branch .LBB0_573

; __device__ __forceinline__ void grid_barrier(unsigned* bar, unsigned& epoch) {
;     asm volatile("s_waitcnt vmcnt(0) lgkmcnt(0)" ::: "memory");
;     __syncthreads();
;     epoch += 1;
;     if (threadIdx.x == 0) {
;         __builtin_amdgcn_fence(__ATOMIC_RELEASE, "agent");
;         asm volatile("s_waitcnt vmcnt(0)" ::: "memory");
;         const unsigned old = __hip_atomic_fetch_add(bar, 1u, __ATOMIC_RELAXED, __HIP_MEMORY_SCOPE_AGENT);
.LBB0_636:
	s_setprio 0
	s_waitcnt vmcnt(0) lgkmcnt(0)
	s_barrier
	s_mov_b64 s[2:3], exec
	v_readlane_b32 s4, v254, 32
	v_readlane_b32 s5, v254, 33
	s_and_b64 s[4:5], s[2:3], s[4:5]
	s_mov_b64 s[58:59], 0x380
	s_mov_b64 s[60:61], 0x100
	s_mov_b64 s[62:63], 0x200
	s_mov_b64 s[64:65], 0x280
	s_mov_b64 exec, s[4:5]
	s_cbranch_execz .LBB0_645
	s_mov_b64 s[4:5], exec
	buffer_wbl2 sc1
	s_waitcnt vmcnt(0)
	s_waitcnt vmcnt(0)
	v_mbcnt_lo_u32_b32 v0, s4, 0
	v_mbcnt_hi_u32_b32 v0, s5, v0
	v_cmp_eq_u32_e32 vcc, 0, v0
	s_and_saveexec_b64 s[6:7], vcc
	s_cbranch_execz .LBB0_639
	s_bcnt1_i32_b64 s4, s[4:5]
	v_mov_b32_e32 v1, s4
	v_readlane_b32 s4, v254, 35
	v_readlane_b32 s5, v254, 36
	s_nop 4
	global_atomic_add v1, v161, v1, s[4:5] sc0
